# natten k-loop rotated: 4-slot rings (one barrier per two tiles), batched mask, per-wave skipping of out-of-band key rows
# baseline (speedup 1.0000x reference)
; #define ATT_LOADK(kt) do { const int k0_ = ATT_KEY0(kt); \
;         _Pragma("unroll") for (int p = 0; p < KPT; ++p) { const int c = tid + 512 * p; if (c < KCH) kr[p] = *(const GAS u32x4*)((const GAS char*)(Kb + (size_t)k0_ * DQK) + (unsigned)(c * 16)); } } while (0)
; #define ATT_LOADV(kt) do { const int k0_ = ATT_KEY0(kt); \
;         _Pragma("unroll") for (int p = 0; p < VPT; ++p) vr[p] = *(const GAS u32x4*)((const GAS char*)(Vb + k0_) + lvo[p]); } while (0)
; #define ATT_STOREK(buf) do { \
;         _Pragma("unroll") for (int p = 0; p < KPT; ++p) { const int c = tid + 512 * p; if (c < KCH) *(LAS u32x4*)(lds + (buf) * KBYTES + (c / CPR) * KS + (c % CPR) * 16) = kr[p]; } } while (0)
; #define ATT_STOREV(buf) do { \
;         _Pragma("unroll") for (int p = 0; p < VPT; ++p) { const int c = tid + 512 * p; *(LAS u32x4*)(lds + VOFF + (buf) * VBYTES + (c >> 3) * VS + (c & 7) * 16) = vr[p]; } } while (0)
; #define ATT_DMAK(kt, slot) do { const int k0_ = ATT_KEY0(kt); \
;         _Pragma("unroll") for (int i_ = 0; i_ < DKPT; ++i_) \
;             __builtin_amdgcn_global_load_lds((const unsigned*)((const char*)(Kb + (size_t)k0_ * DQK) + dko[i_]), (LAS unsigned*)(lds + (slot) * KBYTES + i_ * 8192 + w * 1024), 16, 0, 0); } while (0)
; template <int DQK, int DV, int NAT, int VSHIFT, int COMB> ...
;     ...
;         f32x16 o[DV / 32];
; #pragma unroll
;         for (int dt = 0; dt < DV / 32; ++dt)
; #pragma unroll
;             for (int i = 0; i < 16; ++i) o[dt][i] = 0.f;
;         float l_run = 0.f;
;         f32x16 negm;
; #pragma unroll
;         for (int i = 0; i < 16; ++i) negm[i] = 0.f;
;     ...
;         if (K128) { ATT_DMAK(0, 0); ATT_DMAV(0, 0); ATT_DMAK(1, 1); ATT_DMAV(1, 1); ATT_DMAK(2, 2); asm volatile("s_waitcnt vmcnt(0)" ::: "memory"); }
;         else if (DMA) { ATT_DMAK(0, 0); ATT_DMAV(0, 0); ATT_DMAK(1, 1); asm volatile("s_waitcnt vmcnt(0)" ::: "memory"); }
;         else { ATT_LOADK(0); ATT_STOREK(0); ATT_LOADV(0); ATT_STOREV(0); ATT_LOADK(1); ATT_STOREK(1); }
;         __syncthreads();
;         f32x16 sA0, sA1, sB0, sB1;
;         ATT_QK(sA0, sA1, 0);
;         __syncthreads();
;         for (int kt = 0; kt < nkt; kt += 2) {
;             ATT_STEP(sA0, sA1, sB0, sB1, kt, 0);
;             if (kt + 1 < nkt) ATT_STEP(sB0, sB1, sA0, sA1, kt + 1, 1);
.LBB0_542:
	s_or_b64 exec, exec, s[8:9]
	s_min_u32 s12, s15, 0x78
	s_ashr_i32 s15, s5, 4
	s_mul_hi_i32 s9, s5, 0x108000
	s_mul_i32 s5, s5, 0x108000
	v_readlane_b32 s10, v253, 42
	v_readlane_b32 s11, v253, 43
	s_add_u32 s8, s10, s5
	v_readlane_b32 s5, v255, 4
	s_addc_u32 s9, s11, s9
	s_mul_i32 s5, s5, 0x420000
	v_readlane_b32 s10, v253, 53
	s_add_u32 s5, s10, s5
	v_readlane_b32 s10, v253, 54
	s_addc_u32 s11, s10, 0
	s_mul_i32 s10, s15, 0x4200
	s_mul_hi_i32 s13, s15, 0x4200
	s_add_u32 s10, s5, s10
	s_addc_u32 s11, s11, s13
	s_sub_i32 s5, s12, s14
	s_add_i32 s5, s5, 12
	v_lshl_add_u64 v[142:143], s[8:9], 0, v[140:141]
	s_and_b64 s[8:9], s[0:1], exec
	s_mov_b32 m0, s4
	s_cselect_b32 s5, 4, s5
	s_add_i32 s8, s4, 0x4000
	v_lshl_add_u64 v[144:145], s[10:11], 0, v[138:139]
	global_load_lds_dwordx4 v[142:143], off
	v_writelane_b32 v255, s8, 6
	s_mov_b32 m0, s8
	s_add_i32 s8, s4, 0x2000
	v_lshl_add_u64 v[2:3], v[142:143], 0, s[96:97]
	global_load_lds_dwordx4 v[144:145], off
	s_mov_b32 m0, s8
	v_writelane_b32 v255, s8, 7
	global_load_lds_dwordx4 v[2:3], off
	s_waitcnt vmcnt(0)
	s_waitcnt vmcnt(0) lgkmcnt(0)
	s_barrier
	ds_read_b128 v[2:5], v156
	ds_read_b128 v[6:9], v156 offset:4096
	ds_read_b128 v[10:13], v157
	ds_read_b128 v[14:17], v157 offset:4096
	ds_read_b128 v[18:21], v160
	ds_read_b128 v[22:25], v160 offset:4096
	ds_read_b128 v[26:29], v161
	ds_read_b128 v[30:33], v161 offset:4096
	s_waitcnt lgkmcnt(7)
	v_mfma_f32_32x32x16_bf16 v[50:65], v[2:5], v[114:117], 0
	s_mov_b32 s89, 0
	s_waitcnt lgkmcnt(6)
	v_mfma_f32_32x32x16_bf16 v[66:81], v[6:9], v[114:117], 0
	s_waitcnt lgkmcnt(5)
	v_mfma_f32_32x32x16_bf16 v[50:65], v[10:13], v[118:121], v[50:65]
	s_waitcnt lgkmcnt(4)
	v_mfma_f32_32x32x16_bf16 v[66:81], v[14:17], v[118:121], v[66:81]
	s_waitcnt lgkmcnt(3)
	v_mfma_f32_32x32x16_bf16 v[50:65], v[18:21], v[122:125], v[50:65]
	s_waitcnt lgkmcnt(2)
	v_mfma_f32_32x32x16_bf16 v[66:81], v[22:25], v[122:125], v[66:81]
	s_waitcnt lgkmcnt(1)
	v_mfma_f32_32x32x16_bf16 v[50:65], v[26:29], v[126:129], v[50:65]
	s_waitcnt lgkmcnt(0)
	v_mfma_f32_32x32x16_bf16 v[66:81], v[30:33], v[126:129], v[66:81]
	s_cmp_gt_i32 s5, 0
	s_barrier
	s_cbranch_scc0 .LBB0_532
	v_readlane_b32 s8, v253, 57
	s_add_i32 s7, s8, s7
	s_max_i32 s7, s7, 4
	s_add_i32 s7, s7, -4
	s_min_u32 s91, s7, 0x78
	s_add_i32 s7, s91, 8
	s_and_b64 s[0:1], s[0:1], exec
	v_writelane_b32 v253, s7, 10
	s_cselect_b32 s7, 0, s14
	s_mul_i32 s0, s6, 0xffffff84
	v_writelane_b32 v253, s0, 6
	s_mul_i32 s0, s7, 31
	v_readlane_b32 s1, v254, 47
	v_mov_b32_e32 v2, v1
	v_mov_b32_e32 v3, v1
	v_mov_b32_e32 v4, v1
	v_mov_b32_e32 v5, v1
	v_mov_b32_e32 v6, v1
	v_mov_b32_e32 v7, v1
	v_mov_b32_e32 v8, v1
	v_mov_b32_e32 v9, v1
	v_mov_b32_e32 v10, v1
	v_mov_b32_e32 v11, v1
	v_mov_b32_e32 v12, v1
	v_mov_b32_e32 v13, v1
	v_mov_b32_e32 v14, v1
	v_mov_b32_e32 v15, v1
	v_mov_b32_e32 v16, v1
	v_mov_b32_e32 v17, v1
	v_mov_b32_e32 v18, v1
	v_mov_b32_e32 v19, v1
	v_mov_b32_e32 v20, v1
	v_mov_b32_e32 v21, v1
	v_mov_b32_e32 v22, v1
	v_mov_b32_e32 v23, v1
	v_mov_b32_e32 v24, v1
	v_mov_b32_e32 v25, v1
	v_mov_b32_e32 v26, v1
	v_mov_b32_e32 v27, v1
	v_mov_b32_e32 v28, v1
	v_mov_b32_e32 v29, v1
	v_mov_b32_e32 v30, v1
	v_mov_b32_e32 v31, v1
	s_add_i32 s88, s1, s0
	s_lshl_b32 s0, s7, 6
	v_mov_b32_e32 v0, v1
	v_mov_b64_e32 v[32:33], v[30:31]
	v_writelane_b32 v255, s15, 8
	s_add_i32 s90, s0, 0xc0
	v_mov_b32_e32 v34, v1
	v_mov_b32_e32 v35, v1
	v_mov_b32_e32 v36, v1
	v_mov_b32_e32 v37, v1
	v_mov_b32_e32 v38, v1
	v_mov_b32_e32 v39, v1
	v_mov_b32_e32 v40, v1
	v_mov_b32_e32 v41, v1
	v_mov_b32_e32 v42, v1
	v_mov_b32_e32 v43, v1
	v_mov_b32_e32 v44, v1
	v_mov_b32_e32 v45, v1
	v_mov_b32_e32 v46, v1
	v_mov_b32_e32 v47, v1
	v_mov_b32_e32 v48, v1
	v_mov_b32_e32 v49, v1
	v_mov_b32_e32 v147, 0
	v_mov_b64_e32 v[30:31], v[28:29]
	v_mov_b64_e32 v[28:29], v[26:27]
	v_mov_b64_e32 v[26:27], v[24:25]
	v_mov_b64_e32 v[24:25], v[22:23]
	v_mov_b64_e32 v[22:23], v[20:21]
	v_mov_b64_e32 v[20:21], v[18:19]
	v_mov_b64_e32 v[18:19], v[16:17]
	v_mov_b64_e32 v[16:17], v[14:15]
	v_mov_b64_e32 v[14:15], v[12:13]
	v_mov_b64_e32 v[12:13], v[10:11]
	v_mov_b64_e32 v[10:11], v[8:9]
	v_mov_b64_e32 v[8:9], v[6:7]
	v_mov_b64_e32 v[6:7], v[4:5]
	v_mov_b64_e32 v[4:5], v[2:3]
	v_mov_b64_e32 v[2:3], v[0:1]
	s_mov_b32 s89, -1
	s_add_i32 s12, s89, 2
	s_cmp_ge_u32 s12, s5
	s_cbranch_scc1 .Lnat_dskip1
	s_cmp_gt_u32 s12, 3
	s_cselect_b32 s13, s7, 0
	s_add_i32 s13, s13, s12
	s_lshl_b32 s13, s13, 6
	s_and_b32 s0, s12, 1
	s_lshl_b32 s0, s0, 13
	s_bfe_u32 s1, s12, 0x10001
	s_mul_i32 s1, s1, 0xa000
	s_add_i32 s0, s0, s1
	s_add_i32 s0, s0, 0x4000
	s_add_i32 m0, s4, s0
	s_lshl_b32 s0, s13, 1
	s_mov_b32 s1, 0
	v_lshl_add_u64 v[182:183], v[144:145], 0, s[0:1]
	global_load_lds_dwordx4 v[182:183], off
.Lnat_dskip1:
	s_add_i32 s12, s89, 3
	s_cmp_ge_u32 s12, s5
	s_cbranch_scc1 .Lnat_dskip2
	s_cmp_gt_u32 s12, 3
	s_cselect_b32 s13, s7, 0
	s_add_i32 s13, s13, s12
	s_lshl_b32 s13, s13, 6
	s_and_b32 s0, s12, 1
	s_lshl_b32 s0, s0, 13
	s_bfe_u32 s1, s12, 0x10001
	s_mul_i32 s1, s1, 0xa000
	s_add_i32 s0, s0, s1
	s_add_i32 m0, s4, s0
	s_lshl_b32 s0, s13, 7
	s_mov_b32 s1, 0
	v_lshl_add_u64 v[182:183], v[142:143], 0, s[0:1]
	global_load_lds_dwordx4 v[182:183], off
.Lnat_dskip2:
	s_mov_b32 s89, 0
	s_waitcnt vmcnt(0)
	s_barrier
	s_mov_b64 s[8:9], -1
	s_mov_b64 s[10:11], 0
	s_add_i32 s12, s89, 0
	s_cmp_lt_u32 s12, 4
	s_cbranch_scc1 .Lnat_mdone3
	s_add_i32 s13, s12, s7
	s_add_i32 s13, s13, -4
	s_cmp_lt_i32 s13, s91
	s_cbranch_scc1 .Lnat_mout4
	v_readlane_b32 s0, v253, 10
	s_cmp_ge_i32 s13, s0
	s_cbranch_scc1 .Lnat_mout4
	v_readlane_b32 s0, v253, 6
	v_readlane_b32 s1, v254, 47
	s_add_i32 s0, s0, s1
	s_add_i32 s1, s7, s12
	s_add_i32 s1, s1, -1
	s_mul_i32 s1, s1, 31
	s_add_i32 s0, s0, s1
	v_lshl_add_u32 v178, s0, 2, v150
	v_lshl_add_u32 v178, v151, 2, v178
	v_sub_u32_e32 v176, 0, v150
	v_sub_u32_e64 v176, v176, 32 clamp
	v_min_u32_e32 v176, 0xc0, v176
	v_lshlrev_b32_e32 v177, 2, v151
	v_sub_u32_e32 v176, v177, v176
	ds_read_b32 v130, v178 offset:32828
	ds_read_b32 v131, v178 offset:32832
	ds_read_b32 v132, v178 offset:32836
	ds_read_b32 v133, v178 offset:32840
	ds_read_b32 v134, v178 offset:32844
	ds_read_b32 v135, v178 offset:32848
	ds_read_b32 v136, v178 offset:32852
	ds_read_b32 v137, v178 offset:32856
	ds_read_b32 v146, v178 offset:32892
	ds_read_b32 v148, v178 offset:32896
	ds_read_b32 v149, v178 offset:32900
	ds_read_b32 v166, v178 offset:32904
	ds_read_b32 v167, v178 offset:32908
	ds_read_b32 v168, v178 offset:32912
	ds_read_b32 v169, v178 offset:32916
	ds_read_b32 v0, v178 offset:32920
	s_waitcnt lgkmcnt(8)
	v_add_u32_e32 v184, 0, v176
	v_add_u32_e32 v185, 4, v176
	v_add_u32_e32 v174, 8, v176
	v_add_u32_e32 v175, 12, v176
	v_fmac_f32_e32 v50, 0x3fb8aa3b, v130
	v_fmac_f32_e32 v51, 0x3fb8aa3b, v131
	v_fmac_f32_e32 v52, 0x3fb8aa3b, v132
	v_fmac_f32_e32 v53, 0x3fb8aa3b, v133
	v_cmp_gt_u32_e32 vcc, 64, v184
	v_cmp_gt_u32_e64 s[0:1], 64, v185
	v_cmp_gt_u32_e64 s[12:13], 64, v174
	v_cmp_gt_u32_e64 s[14:15], 64, v175
	v_cndmask_b32_e32 v50, v205, v50, vcc
	v_cndmask_b32_e64 v51, v205, v51, s[0:1]
	v_cndmask_b32_e64 v52, v205, v52, s[12:13]
	v_cndmask_b32_e64 v53, v205, v53, s[14:15]
	v_add_u32_e32 v184, 16, v176
	v_add_u32_e32 v185, 20, v176
	v_add_u32_e32 v174, 24, v176
	v_add_u32_e32 v175, 28, v176
	v_fmac_f32_e32 v54, 0x3fb8aa3b, v134
	v_fmac_f32_e32 v55, 0x3fb8aa3b, v135
	v_fmac_f32_e32 v56, 0x3fb8aa3b, v136
	v_fmac_f32_e32 v57, 0x3fb8aa3b, v137
	v_cmp_gt_u32_e32 vcc, 64, v184
	v_cmp_gt_u32_e64 s[0:1], 64, v185
	v_cmp_gt_u32_e64 s[12:13], 64, v174
	v_cmp_gt_u32_e64 s[14:15], 64, v175
	v_cndmask_b32_e32 v54, v205, v54, vcc
	v_cndmask_b32_e64 v55, v205, v55, s[0:1]
	v_cndmask_b32_e64 v56, v205, v56, s[12:13]
	v_cndmask_b32_e64 v57, v205, v57, s[14:15]
	ds_read_b32 v130, v178 offset:32956
	ds_read_b32 v131, v178 offset:32960
	ds_read_b32 v132, v178 offset:32964
	ds_read_b32 v133, v178 offset:32968
	ds_read_b32 v134, v178 offset:32972
	ds_read_b32 v135, v178 offset:32976
	ds_read_b32 v136, v178 offset:32980
	ds_read_b32 v137, v178 offset:32984
	s_waitcnt lgkmcnt(8)
	v_add_u32_e32 v184, 64, v176
	v_add_u32_e32 v185, 68, v176
	v_add_u32_e32 v174, 72, v176
	v_add_u32_e32 v175, 76, v176
	v_fmac_f32_e32 v58, 0x3fb8aa3b, v146
	v_fmac_f32_e32 v59, 0x3fb8aa3b, v148
	v_fmac_f32_e32 v60, 0x3fb8aa3b, v149
	v_fmac_f32_e32 v61, 0x3fb8aa3b, v166
	v_cmp_gt_u32_e32 vcc, 64, v184
	v_cmp_gt_u32_e64 s[0:1], 64, v185
	v_cmp_gt_u32_e64 s[12:13], 64, v174
	v_cmp_gt_u32_e64 s[14:15], 64, v175
	v_cndmask_b32_e32 v58, v205, v58, vcc
	v_cndmask_b32_e64 v59, v205, v59, s[0:1]
	v_cndmask_b32_e64 v60, v205, v60, s[12:13]
	v_cndmask_b32_e64 v61, v205, v61, s[14:15]
	v_add_u32_e32 v184, 80, v176
	v_add_u32_e32 v185, 84, v176
	v_add_u32_e32 v174, 88, v176
	v_add_u32_e32 v175, 92, v176
	v_fmac_f32_e32 v62, 0x3fb8aa3b, v167
	v_fmac_f32_e32 v63, 0x3fb8aa3b, v168
	v_fmac_f32_e32 v64, 0x3fb8aa3b, v169
	v_fmac_f32_e32 v65, 0x3fb8aa3b, v0
	v_cmp_gt_u32_e32 vcc, 64, v184
	v_cmp_gt_u32_e64 s[0:1], 64, v185
	v_cmp_gt_u32_e64 s[12:13], 64, v174
	v_cmp_gt_u32_e64 s[14:15], 64, v175
	v_cndmask_b32_e32 v62, v205, v62, vcc
	v_cndmask_b32_e64 v63, v205, v63, s[0:1]
	v_cndmask_b32_e64 v64, v205, v64, s[12:13]
	v_cndmask_b32_e64 v65, v205, v65, s[14:15]
	ds_read_b32 v146, v178 offset:33020
	ds_read_b32 v148, v178 offset:33024
	ds_read_b32 v149, v178 offset:33028
	ds_read_b32 v166, v178 offset:33032
	ds_read_b32 v167, v178 offset:33036
	ds_read_b32 v168, v178 offset:33040
	ds_read_b32 v169, v178 offset:33044
	ds_read_b32 v0, v178 offset:33048
	s_waitcnt lgkmcnt(8)
	v_add_u32_e32 v184, 128, v176
	v_add_u32_e32 v185, 132, v176
	v_add_u32_e32 v174, 136, v176
	v_add_u32_e32 v175, 140, v176
	v_fmac_f32_e32 v66, 0x3fb8aa3b, v130
	v_fmac_f32_e32 v67, 0x3fb8aa3b, v131
	v_fmac_f32_e32 v68, 0x3fb8aa3b, v132
	v_fmac_f32_e32 v69, 0x3fb8aa3b, v133
	v_cmp_gt_u32_e32 vcc, 64, v184
	v_cmp_gt_u32_e64 s[0:1], 64, v185
	v_cmp_gt_u32_e64 s[12:13], 64, v174
	v_cmp_gt_u32_e64 s[14:15], 64, v175
	v_cndmask_b32_e32 v66, v205, v66, vcc
	v_cndmask_b32_e64 v67, v205, v67, s[0:1]
	v_cndmask_b32_e64 v68, v205, v68, s[12:13]
	v_cndmask_b32_e64 v69, v205, v69, s[14:15]
	v_add_u32_e32 v184, 144, v176
	v_add_u32_e32 v185, 148, v176
	v_add_u32_e32 v174, 152, v176
	v_add_u32_e32 v175, 156, v176
	v_fmac_f32_e32 v70, 0x3fb8aa3b, v134
	v_fmac_f32_e32 v71, 0x3fb8aa3b, v135
	v_fmac_f32_e32 v72, 0x3fb8aa3b, v136
	v_fmac_f32_e32 v73, 0x3fb8aa3b, v137
	v_cmp_gt_u32_e32 vcc, 64, v184
	v_cmp_gt_u32_e64 s[0:1], 64, v185
	v_cmp_gt_u32_e64 s[12:13], 64, v174
	v_cmp_gt_u32_e64 s[14:15], 64, v175
	v_cndmask_b32_e32 v70, v205, v70, vcc
	v_cndmask_b32_e64 v71, v205, v71, s[0:1]
	v_cndmask_b32_e64 v72, v205, v72, s[12:13]
	v_cndmask_b32_e64 v73, v205, v73, s[14:15]
	s_waitcnt lgkmcnt(0)
	v_add_u32_e32 v184, 192, v176
	v_add_u32_e32 v185, 196, v176
	v_add_u32_e32 v174, 200, v176
	v_add_u32_e32 v175, 204, v176
	v_fmac_f32_e32 v74, 0x3fb8aa3b, v146
	v_fmac_f32_e32 v75, 0x3fb8aa3b, v148
	v_fmac_f32_e32 v76, 0x3fb8aa3b, v149
	v_fmac_f32_e32 v77, 0x3fb8aa3b, v166
	v_cmp_gt_u32_e32 vcc, 64, v184
	v_cmp_gt_u32_e64 s[0:1], 64, v185
	v_cmp_gt_u32_e64 s[12:13], 64, v174
	v_cmp_gt_u32_e64 s[14:15], 64, v175
	v_cndmask_b32_e32 v74, v205, v74, vcc
	v_cndmask_b32_e64 v75, v205, v75, s[0:1]
	v_cndmask_b32_e64 v76, v205, v76, s[12:13]
	v_cndmask_b32_e64 v77, v205, v77, s[14:15]
	v_add_u32_e32 v184, 208, v176
	v_add_u32_e32 v185, 212, v176
	v_add_u32_e32 v174, 216, v176
	v_add_u32_e32 v175, 220, v176
	v_fmac_f32_e32 v78, 0x3fb8aa3b, v167
	v_fmac_f32_e32 v79, 0x3fb8aa3b, v168
	v_fmac_f32_e32 v80, 0x3fb8aa3b, v169
	v_fmac_f32_e32 v81, 0x3fb8aa3b, v0
	v_cmp_gt_u32_e32 vcc, 64, v184
	v_cmp_gt_u32_e64 s[0:1], 64, v185
	v_cmp_gt_u32_e64 s[12:13], 64, v174
	v_cmp_gt_u32_e64 s[14:15], 64, v175
	v_cndmask_b32_e32 v78, v205, v78, vcc
	v_cndmask_b32_e64 v79, v205, v79, s[0:1]
	v_cndmask_b32_e64 v80, v205, v80, s[12:13]
	v_cndmask_b32_e64 v81, v205, v81, s[14:15]
	s_branch .Lnat_mdone3

.Lnat_mdone3:
.Lnatv_pre_top:
	v_exp_f32_e32 v130, v50
	v_exp_f32_e32 v131, v51
	v_exp_f32_e32 v132, v66
	v_exp_f32_e32 v133, v67
	v_add_f32_e32 v146, 0, v130
	v_add_f32_e32 v149, 0, v131
	v_cvt_pk_bf16_f32 v82, v130, v131
	v_exp_f32_e32 v134, v52
	v_exp_f32_e32 v135, v53
	v_add_f32_e32 v148, 0, v132
	v_add_f32_e32 v166, 0, v133
	v_cvt_pk_bf16_f32 v90, v132, v133
	v_exp_f32_e32 v136, v68
	v_exp_f32_e32 v137, v69
	v_add_f32_e32 v146, v134, v146
	v_add_f32_e32 v149, v135, v149
	v_cvt_pk_bf16_f32 v83, v134, v135
	v_exp_f32_e32 v130, v54
	v_exp_f32_e32 v131, v55
	v_add_f32_e32 v148, v136, v148
	v_add_f32_e32 v166, v137, v166
	v_cvt_pk_bf16_f32 v91, v136, v137
	v_exp_f32_e32 v132, v70
	v_exp_f32_e32 v133, v71
	v_add_f32_e32 v146, v130, v146
	v_add_f32_e32 v149, v131, v149
	v_cvt_pk_bf16_f32 v84, v130, v131
	v_exp_f32_e32 v134, v56
	v_exp_f32_e32 v135, v57
	v_add_f32_e32 v148, v132, v148
	v_add_f32_e32 v166, v133, v166
	v_cvt_pk_bf16_f32 v92, v132, v133
	v_exp_f32_e32 v136, v72
	v_exp_f32_e32 v137, v73
	v_add_f32_e32 v146, v134, v146
	v_add_f32_e32 v149, v135, v149
	v_cvt_pk_bf16_f32 v85, v134, v135
	v_exp_f32_e32 v130, v58
	v_exp_f32_e32 v131, v59
	v_add_f32_e32 v148, v136, v148
	v_add_f32_e32 v166, v137, v166
	v_cvt_pk_bf16_f32 v93, v136, v137
	v_exp_f32_e32 v132, v74
	v_exp_f32_e32 v133, v75
	v_add_f32_e32 v146, v130, v146
	v_add_f32_e32 v149, v131, v149
	v_cvt_pk_bf16_f32 v86, v130, v131
	v_exp_f32_e32 v134, v60
	v_exp_f32_e32 v135, v61
	v_add_f32_e32 v148, v132, v148
	v_add_f32_e32 v166, v133, v166
	v_cvt_pk_bf16_f32 v94, v132, v133
	v_exp_f32_e32 v136, v76
	v_exp_f32_e32 v137, v77
	v_add_f32_e32 v146, v134, v146
	v_add_f32_e32 v149, v135, v149
	v_cvt_pk_bf16_f32 v87, v134, v135
	v_exp_f32_e32 v130, v62
	v_exp_f32_e32 v131, v63
	v_add_f32_e32 v148, v136, v148
	v_add_f32_e32 v166, v137, v166
	v_cvt_pk_bf16_f32 v95, v136, v137
	v_exp_f32_e32 v132, v78
	v_exp_f32_e32 v133, v79
	v_add_f32_e32 v146, v130, v146
	v_add_f32_e32 v149, v131, v149
	v_cvt_pk_bf16_f32 v88, v130, v131
	v_exp_f32_e32 v134, v64
	v_exp_f32_e32 v135, v65
	v_add_f32_e32 v148, v132, v148
	v_add_f32_e32 v166, v133, v166
	v_cvt_pk_bf16_f32 v96, v132, v133
	v_exp_f32_e32 v136, v80
	v_exp_f32_e32 v137, v81
	v_add_f32_e32 v146, v134, v146
	v_add_f32_e32 v149, v135, v149
	v_cvt_pk_bf16_f32 v89, v134, v135
	s_nop 0
	v_add_f32_e32 v148, v136, v148
	v_add_f32_e32 v166, v137, v166
	v_cvt_pk_bf16_f32 v97, v136, v137
	v_add_f32_e32 v146, v146, v149
	v_add_f32_e32 v148, v148, v166
	v_add_f32_e32 v167, v146, v148
	s_nop 0
	v_cmp_ngt_f32_e32 vcc, s72, v167
	s_nop 1
	s_or_b64 vcc, vcc, s[8:9]
	s_andn2_b64 vcc, vcc, s[10:11]
	s_cbranch_vccz .Lnatv_pre_fast
	v_max3_f32 v168, v50, v51, v52
	v_max3_f32 v168, v168, v53, v54
	v_max3_f32 v168, v168, v55, v56
	v_max3_f32 v168, v168, v57, v58
	v_max3_f32 v168, v168, v59, v60
	v_max3_f32 v168, v168, v61, v62
	v_max3_f32 v168, v168, v63, v64
	v_max3_f32 v168, v168, v65, v66
	v_max3_f32 v168, v168, v67, v68
	v_max3_f32 v168, v168, v69, v70
	v_max3_f32 v168, v168, v71, v72
	v_max3_f32 v168, v168, v73, v74
	v_max3_f32 v168, v168, v75, v76
	v_max3_f32 v168, v168, v77, v78
	v_max3_f32 v168, v168, v79, v80
	v_max_f32_e32 v168, v168, v81
	ds_bpermute_b32 v169, v152, v168
	s_waitcnt lgkmcnt(0)
	v_max_f32_e32 v168, v168, v169
	s_and_b64 vcc, exec, s[8:9]
	s_cbranch_vccnz .Lnatv_pre_anchor
	v_max_f32_e32 v168, 0, v168
	v_exp_f32_e64 v0, -v168
	s_nop 7
	s_nop 7
	v_mul_f32_e32 v147, v147, v0
	v_mul_f32_e32 v2, v2, v0
	v_mul_f32_e32 v3, v3, v0
	v_mul_f32_e32 v4, v4, v0
	v_mul_f32_e32 v5, v5, v0
	v_mul_f32_e32 v6, v6, v0
	v_mul_f32_e32 v7, v7, v0
	v_mul_f32_e32 v8, v8, v0
	v_mul_f32_e32 v9, v9, v0
	v_mul_f32_e32 v10, v10, v0
	v_mul_f32_e32 v11, v11, v0
	v_mul_f32_e32 v12, v12, v0
	v_mul_f32_e32 v13, v13, v0
	v_mul_f32_e32 v14, v14, v0
	v_mul_f32_e32 v15, v15, v0
	v_mul_f32_e32 v16, v16, v0
	v_mul_f32_e32 v17, v17, v0
	v_mul_f32_e32 v18, v18, v0
	v_mul_f32_e32 v19, v19, v0
	v_mul_f32_e32 v20, v20, v0
	v_mul_f32_e32 v21, v21, v0
	v_mul_f32_e32 v22, v22, v0
	v_mul_f32_e32 v23, v23, v0
	v_mul_f32_e32 v24, v24, v0
	v_mul_f32_e32 v25, v25, v0
	v_mul_f32_e32 v26, v26, v0
	v_mul_f32_e32 v27, v27, v0
	v_mul_f32_e32 v28, v28, v0
	v_mul_f32_e32 v29, v29, v0
	v_mul_f32_e32 v30, v30, v0
	v_mul_f32_e32 v31, v31, v0
	v_mul_f32_e32 v32, v32, v0
	v_mul_f32_e32 v33, v33, v0
.Lnatv_pre_anchor:
	v_sub_f32_e32 v50, v50, v168
	v_sub_f32_e32 v51, v51, v168
	v_sub_f32_e32 v52, v52, v168
	v_sub_f32_e32 v53, v53, v168
	v_sub_f32_e32 v54, v54, v168
	v_sub_f32_e32 v55, v55, v168
	v_sub_f32_e32 v56, v56, v168
	v_sub_f32_e32 v57, v57, v168
	v_sub_f32_e32 v58, v58, v168
	v_sub_f32_e32 v59, v59, v168
	v_sub_f32_e32 v60, v60, v168
	v_sub_f32_e32 v61, v61, v168
	v_sub_f32_e32 v62, v62, v168
	v_sub_f32_e32 v63, v63, v168
	v_sub_f32_e32 v64, v64, v168
	v_sub_f32_e32 v65, v65, v168
	v_sub_f32_e32 v66, v66, v168
	v_sub_f32_e32 v67, v67, v168
	v_sub_f32_e32 v68, v68, v168
	v_sub_f32_e32 v69, v69, v168
	v_sub_f32_e32 v70, v70, v168
	v_sub_f32_e32 v71, v71, v168
	v_sub_f32_e32 v72, v72, v168
	v_sub_f32_e32 v73, v73, v168
	v_sub_f32_e32 v74, v74, v168
	v_sub_f32_e32 v75, v75, v168
	v_sub_f32_e32 v76, v76, v168
	v_sub_f32_e32 v77, v77, v168
	v_sub_f32_e32 v78, v78, v168
	v_sub_f32_e32 v79, v79, v168
	v_sub_f32_e32 v80, v80, v168
	v_sub_f32_e32 v81, v81, v168
	v_sub_f32_e32 v34, v34, v168
	v_sub_f32_e32 v35, v35, v168
	v_sub_f32_e32 v36, v36, v168
	v_sub_f32_e32 v37, v37, v168
	v_sub_f32_e32 v38, v38, v168
	v_sub_f32_e32 v39, v39, v168
	v_sub_f32_e32 v40, v40, v168
	v_sub_f32_e32 v41, v41, v168
	v_sub_f32_e32 v42, v42, v168
	v_sub_f32_e32 v43, v43, v168
	v_sub_f32_e32 v44, v44, v168
	v_sub_f32_e32 v45, v45, v168
	v_sub_f32_e32 v46, v46, v168
	v_sub_f32_e32 v47, v47, v168
	v_sub_f32_e32 v48, v48, v168
	v_sub_f32_e32 v49, v49, v168
	s_mov_b64 s[10:11], -1
	s_branch .Lnatv_pre_top
.Lnatv_pre_fast:
	v_add_f32_e32 v147, v147, v167
	.p2align 6

.Lnat_dskip5:
	s_add_i32 s12, s89, 4
	s_cmp_ge_u32 s12, s5
	s_cbranch_scc1 .Lnat_dskip6
	s_cmp_gt_u32 s12, 3
	s_cselect_b32 s13, s7, 0
	s_add_i32 s13, s13, s12
	s_lshl_b32 s13, s13, 6
	s_and_b32 s0, s12, 1
	s_lshl_b32 s0, s0, 13
	s_bfe_u32 s1, s12, 0x10001
	s_mul_i32 s1, s1, 0xa000
	s_add_i32 s0, s0, s1
	s_add_i32 m0, s4, s0
	s_lshl_b32 s0, s13, 7
	s_mov_b32 s1, 0
	v_lshl_add_u64 v[182:183], v[142:143], 0, s[0:1]
	global_load_lds_dwordx4 v[182:183], off
.Lnat_dskip6:
	s_add_i32 s12, s89, 1
	s_cmp_ge_u32 s12, s5
	s_cbranch_scc1 .Lnat_noqk7
	s_add_i32 s12, s89, 1
	s_cmp_lt_u32 s12, 4
	s_cbranch_scc1 .Lnat_act9
	s_add_i32 s12, s12, s7
	s_add_i32 s12, s12, -4
	s_cmp_lt_i32 s12, s91
	s_cbranch_scc1 .Lnat_noqk7
	v_readlane_b32 s13, v253, 10
	s_cmp_ge_i32 s12, s13
	s_cbranch_scc1 .Lnat_noqk7
.Lnat_act9:
	s_add_i32 s12, s89, 1
	s_and_b32 s0, s12, 1
	s_lshl_b32 s0, s0, 13
	s_bfe_u32 s1, s12, 0x10001
	s_mul_i32 s1, s1, 0xa000
	s_add_i32 s0, s0, s1
	v_add_u32_e32 v174, s0, v156
	v_add_u32_e32 v175, s0, v157
	v_add_u32_e32 v176, s0, v160
	v_add_u32_e32 v177, s0, v161
	ds_read_b128 v[98:101], v174
	ds_read_b128 v[102:105], v174 offset:4096
	ds_read_b128 v[106:109], v175
	ds_read_b128 v[110:113], v175 offset:4096
	s_setprio 1
	s_waitcnt lgkmcnt(3)
	v_mfma_f32_32x32x16_bf16 v[50:65], v[98:101], v[114:117], v[34:49]
	ds_read_b128 v[98:101], v176
	s_waitcnt lgkmcnt(3)
	v_mfma_f32_32x32x16_bf16 v[66:81], v[102:105], v[114:117], v[34:49]
	ds_read_b128 v[102:105], v176 offset:4096
	s_waitcnt lgkmcnt(3)
	v_mfma_f32_32x32x16_bf16 v[50:65], v[106:109], v[118:121], v[50:65]
	ds_read_b128 v[106:109], v177
	s_waitcnt lgkmcnt(3)
	v_mfma_f32_32x32x16_bf16 v[66:81], v[110:113], v[118:121], v[66:81]
	ds_read_b128 v[110:113], v177 offset:4096
	s_waitcnt lgkmcnt(3)
	v_mfma_f32_32x32x16_bf16 v[50:65], v[98:101], v[122:125], v[50:65]
	s_waitcnt lgkmcnt(2)
	v_mfma_f32_32x32x16_bf16 v[66:81], v[102:105], v[122:125], v[66:81]
	s_waitcnt lgkmcnt(1)
	v_mfma_f32_32x32x16_bf16 v[50:65], v[106:109], v[126:129], v[50:65]
	s_waitcnt lgkmcnt(0)
	v_mfma_f32_32x32x16_bf16 v[66:81], v[110:113], v[126:129], v[66:81]
	s_setprio 0
.Lnat_noqk7:
	s_add_i32 s12, s89, 0
	s_cmp_lt_u32 s12, 4
	s_cbranch_scc1 .Lnat_act10
	s_add_i32 s12, s12, s7
	s_add_i32 s12, s12, -4
	s_cmp_lt_i32 s12, s91
	s_cbranch_scc1 .Lnat_nopv8
	v_readlane_b32 s13, v253, 10
	s_cmp_ge_i32 s12, s13
	s_cbranch_scc1 .Lnat_nopv8
.Lnat_act10:
	s_add_i32 s12, s89, 0
	s_and_b32 s0, s12, 1
	s_lshl_b32 s0, s0, 13
	s_bfe_u32 s1, s12, 0x10001
	s_mul_i32 s1, s1, 0xa000
	s_add_i32 s0, s0, s1
	s_add_i32 s0, s0, 0x4000
	v_add_u32_e32 v178, s0, v162
	v_add_u32_e32 v179, s0, v163
	v_add_u32_e32 v180, s0, v164
	v_add_u32_e32 v181, s0, v165
	ds_read_b128 v[98:101], v178
	ds_read_b128 v[102:105], v178 offset:4096
	ds_read_b128 v[106:109], v179
	ds_read_b128 v[110:113], v179 offset:4096
	s_setprio 1
	s_waitcnt lgkmcnt(3)
	v_mfma_f32_32x32x16_bf16 v[2:17], v[98:101], v[82:85], v[2:17]
	ds_read_b128 v[98:101], v180
	s_waitcnt lgkmcnt(3)
	v_mfma_f32_32x32x16_bf16 v[18:33], v[102:105], v[82:85], v[18:33]
	ds_read_b128 v[102:105], v180 offset:4096
	s_waitcnt lgkmcnt(3)
	v_mfma_f32_32x32x16_bf16 v[2:17], v[106:109], v[86:89], v[2:17]
	ds_read_b128 v[106:109], v181
	s_waitcnt lgkmcnt(3)
	v_mfma_f32_32x32x16_bf16 v[18:33], v[110:113], v[86:89], v[18:33]
	ds_read_b128 v[110:113], v181 offset:4096
	s_waitcnt lgkmcnt(3)
	v_mfma_f32_32x32x16_bf16 v[2:17], v[98:101], v[90:93], v[2:17]
	s_waitcnt lgkmcnt(2)
	v_mfma_f32_32x32x16_bf16 v[18:33], v[102:105], v[90:93], v[18:33]
	s_waitcnt lgkmcnt(1)
	v_mfma_f32_32x32x16_bf16 v[2:17], v[106:109], v[94:97], v[2:17]
	s_waitcnt lgkmcnt(0)
	v_mfma_f32_32x32x16_bf16 v[18:33], v[110:113], v[94:97], v[18:33]
	s_setprio 0

.Lnat_act12:
	s_mov_b64 s[8:9], 0
	s_mov_b64 s[10:11], 0
	s_add_i32 s12, s89, 1
	s_cmp_lt_u32 s12, 4
	s_cbranch_scc1 .Lnat_mdone13
	s_add_i32 s13, s12, s7
	s_add_i32 s13, s13, -4
	s_cmp_lt_i32 s13, s91
	s_cbranch_scc1 .Lnat_mout14
	v_readlane_b32 s0, v253, 10
	s_cmp_ge_i32 s13, s0
	s_cbranch_scc1 .Lnat_mout14
	v_readlane_b32 s0, v253, 6
	v_readlane_b32 s1, v254, 47
	s_add_i32 s0, s0, s1
	s_add_i32 s1, s7, s12
	s_add_i32 s1, s1, -1
	s_mul_i32 s1, s1, 31
	s_add_i32 s0, s0, s1
	v_lshl_add_u32 v178, s0, 2, v150
	v_lshl_add_u32 v178, v151, 2, v178
	v_sub_u32_e32 v176, 0, v150
	v_sub_u32_e64 v176, v176, 32 clamp
	v_min_u32_e32 v176, 0xc0, v176
	v_lshlrev_b32_e32 v177, 2, v151
	v_sub_u32_e32 v176, v177, v176
	ds_read_b32 v130, v178 offset:32828
	ds_read_b32 v131, v178 offset:32832
	ds_read_b32 v132, v178 offset:32836
	ds_read_b32 v133, v178 offset:32840
	ds_read_b32 v134, v178 offset:32844
	ds_read_b32 v135, v178 offset:32848
	ds_read_b32 v136, v178 offset:32852
	ds_read_b32 v137, v178 offset:32856
	ds_read_b32 v146, v178 offset:32892
	ds_read_b32 v148, v178 offset:32896
	ds_read_b32 v149, v178 offset:32900
	ds_read_b32 v166, v178 offset:32904
	ds_read_b32 v167, v178 offset:32908
	ds_read_b32 v168, v178 offset:32912
	ds_read_b32 v169, v178 offset:32916
	ds_read_b32 v0, v178 offset:32920
	s_waitcnt lgkmcnt(8)
	v_add_u32_e32 v184, 0, v176
	v_add_u32_e32 v185, 4, v176
	v_add_u32_e32 v174, 8, v176
	v_add_u32_e32 v175, 12, v176
	v_fmac_f32_e32 v50, 0x3fb8aa3b, v130
	v_fmac_f32_e32 v51, 0x3fb8aa3b, v131
	v_fmac_f32_e32 v52, 0x3fb8aa3b, v132
	v_fmac_f32_e32 v53, 0x3fb8aa3b, v133
	v_cmp_gt_u32_e32 vcc, 64, v184
	v_cmp_gt_u32_e64 s[0:1], 64, v185
	v_cmp_gt_u32_e64 s[12:13], 64, v174
	v_cmp_gt_u32_e64 s[14:15], 64, v175
	v_cndmask_b32_e32 v50, v205, v50, vcc
	v_cndmask_b32_e64 v51, v205, v51, s[0:1]
	v_cndmask_b32_e64 v52, v205, v52, s[12:13]
	v_cndmask_b32_e64 v53, v205, v53, s[14:15]
	v_add_u32_e32 v184, 16, v176
	v_add_u32_e32 v185, 20, v176
	v_add_u32_e32 v174, 24, v176
	v_add_u32_e32 v175, 28, v176
	v_fmac_f32_e32 v54, 0x3fb8aa3b, v134
	v_fmac_f32_e32 v55, 0x3fb8aa3b, v135
	v_fmac_f32_e32 v56, 0x3fb8aa3b, v136
	v_fmac_f32_e32 v57, 0x3fb8aa3b, v137
	v_cmp_gt_u32_e32 vcc, 64, v184
	v_cmp_gt_u32_e64 s[0:1], 64, v185
	v_cmp_gt_u32_e64 s[12:13], 64, v174
	v_cmp_gt_u32_e64 s[14:15], 64, v175
	v_cndmask_b32_e32 v54, v205, v54, vcc
	v_cndmask_b32_e64 v55, v205, v55, s[0:1]
	v_cndmask_b32_e64 v56, v205, v56, s[12:13]
	v_cndmask_b32_e64 v57, v205, v57, s[14:15]
	ds_read_b32 v130, v178 offset:32956
	ds_read_b32 v131, v178 offset:32960
	ds_read_b32 v132, v178 offset:32964
	ds_read_b32 v133, v178 offset:32968
	ds_read_b32 v134, v178 offset:32972
	ds_read_b32 v135, v178 offset:32976
	ds_read_b32 v136, v178 offset:32980
	ds_read_b32 v137, v178 offset:32984
	s_waitcnt lgkmcnt(8)
	v_add_u32_e32 v184, 64, v176
	v_add_u32_e32 v185, 68, v176
	v_add_u32_e32 v174, 72, v176
	v_add_u32_e32 v175, 76, v176
	v_fmac_f32_e32 v58, 0x3fb8aa3b, v146
	v_fmac_f32_e32 v59, 0x3fb8aa3b, v148
	v_fmac_f32_e32 v60, 0x3fb8aa3b, v149
	v_fmac_f32_e32 v61, 0x3fb8aa3b, v166
	v_cmp_gt_u32_e32 vcc, 64, v184
	v_cmp_gt_u32_e64 s[0:1], 64, v185
	v_cmp_gt_u32_e64 s[12:13], 64, v174
	v_cmp_gt_u32_e64 s[14:15], 64, v175
	v_cndmask_b32_e32 v58, v205, v58, vcc
	v_cndmask_b32_e64 v59, v205, v59, s[0:1]
	v_cndmask_b32_e64 v60, v205, v60, s[12:13]
	v_cndmask_b32_e64 v61, v205, v61, s[14:15]
	v_add_u32_e32 v184, 80, v176
	v_add_u32_e32 v185, 84, v176
	v_add_u32_e32 v174, 88, v176
	v_add_u32_e32 v175, 92, v176
	v_fmac_f32_e32 v62, 0x3fb8aa3b, v167
	v_fmac_f32_e32 v63, 0x3fb8aa3b, v168
	v_fmac_f32_e32 v64, 0x3fb8aa3b, v169
	v_fmac_f32_e32 v65, 0x3fb8aa3b, v0
	v_cmp_gt_u32_e32 vcc, 64, v184
	v_cmp_gt_u32_e64 s[0:1], 64, v185
	v_cmp_gt_u32_e64 s[12:13], 64, v174
	v_cmp_gt_u32_e64 s[14:15], 64, v175
	v_cndmask_b32_e32 v62, v205, v62, vcc
	v_cndmask_b32_e64 v63, v205, v63, s[0:1]
	v_cndmask_b32_e64 v64, v205, v64, s[12:13]
	v_cndmask_b32_e64 v65, v205, v65, s[14:15]
	ds_read_b32 v146, v178 offset:33020
	ds_read_b32 v148, v178 offset:33024
	ds_read_b32 v149, v178 offset:33028
	ds_read_b32 v166, v178 offset:33032
	ds_read_b32 v167, v178 offset:33036
	ds_read_b32 v168, v178 offset:33040
	ds_read_b32 v169, v178 offset:33044
	ds_read_b32 v0, v178 offset:33048
	s_waitcnt lgkmcnt(8)
	v_add_u32_e32 v184, 128, v176
	v_add_u32_e32 v185, 132, v176
	v_add_u32_e32 v174, 136, v176
	v_add_u32_e32 v175, 140, v176
	v_fmac_f32_e32 v66, 0x3fb8aa3b, v130
	v_fmac_f32_e32 v67, 0x3fb8aa3b, v131
	v_fmac_f32_e32 v68, 0x3fb8aa3b, v132
	v_fmac_f32_e32 v69, 0x3fb8aa3b, v133
	v_cmp_gt_u32_e32 vcc, 64, v184
	v_cmp_gt_u32_e64 s[0:1], 64, v185
	v_cmp_gt_u32_e64 s[12:13], 64, v174
	v_cmp_gt_u32_e64 s[14:15], 64, v175
	v_cndmask_b32_e32 v66, v205, v66, vcc
	v_cndmask_b32_e64 v67, v205, v67, s[0:1]
	v_cndmask_b32_e64 v68, v205, v68, s[12:13]
	v_cndmask_b32_e64 v69, v205, v69, s[14:15]
	v_add_u32_e32 v184, 144, v176
	v_add_u32_e32 v185, 148, v176
	v_add_u32_e32 v174, 152, v176
	v_add_u32_e32 v175, 156, v176
	v_fmac_f32_e32 v70, 0x3fb8aa3b, v134
	v_fmac_f32_e32 v71, 0x3fb8aa3b, v135
	v_fmac_f32_e32 v72, 0x3fb8aa3b, v136
	v_fmac_f32_e32 v73, 0x3fb8aa3b, v137
	v_cmp_gt_u32_e32 vcc, 64, v184
	v_cmp_gt_u32_e64 s[0:1], 64, v185
	v_cmp_gt_u32_e64 s[12:13], 64, v174
	v_cmp_gt_u32_e64 s[14:15], 64, v175
	v_cndmask_b32_e32 v70, v205, v70, vcc
	v_cndmask_b32_e64 v71, v205, v71, s[0:1]
	v_cndmask_b32_e64 v72, v205, v72, s[12:13]
	v_cndmask_b32_e64 v73, v205, v73, s[14:15]
	s_waitcnt lgkmcnt(0)
	v_add_u32_e32 v184, 192, v176
	v_add_u32_e32 v185, 196, v176
	v_add_u32_e32 v174, 200, v176
	v_add_u32_e32 v175, 204, v176
	v_fmac_f32_e32 v74, 0x3fb8aa3b, v146
	v_fmac_f32_e32 v75, 0x3fb8aa3b, v148
	v_fmac_f32_e32 v76, 0x3fb8aa3b, v149
	v_fmac_f32_e32 v77, 0x3fb8aa3b, v166
	v_cmp_gt_u32_e32 vcc, 64, v184
	v_cmp_gt_u32_e64 s[0:1], 64, v185
	v_cmp_gt_u32_e64 s[12:13], 64, v174
	v_cmp_gt_u32_e64 s[14:15], 64, v175
	v_cndmask_b32_e32 v74, v205, v74, vcc
	v_cndmask_b32_e64 v75, v205, v75, s[0:1]
	v_cndmask_b32_e64 v76, v205, v76, s[12:13]
	v_cndmask_b32_e64 v77, v205, v77, s[14:15]
	v_add_u32_e32 v184, 208, v176
	v_add_u32_e32 v185, 212, v176
	v_add_u32_e32 v174, 216, v176
	v_add_u32_e32 v175, 220, v176
	v_fmac_f32_e32 v78, 0x3fb8aa3b, v167
	v_fmac_f32_e32 v79, 0x3fb8aa3b, v168
	v_fmac_f32_e32 v80, 0x3fb8aa3b, v169
	v_fmac_f32_e32 v81, 0x3fb8aa3b, v0
	v_cmp_gt_u32_e32 vcc, 64, v184
	v_cmp_gt_u32_e64 s[0:1], 64, v185
	v_cmp_gt_u32_e64 s[12:13], 64, v174
	v_cmp_gt_u32_e64 s[14:15], 64, v175
	v_cndmask_b32_e32 v78, v205, v78, vcc
	v_cndmask_b32_e64 v79, v205, v79, s[0:1]
	v_cndmask_b32_e64 v80, v205, v80, s[12:13]
	v_cndmask_b32_e64 v81, v205, v81, s[14:15]
	s_branch .Lnat_mdone13

.Lnatv_mid_fast:
	v_add_f32_e32 v147, v147, v167
.Lnat_vskip11:
	s_add_i32 s12, s89, 2
	s_cmp_ge_u32 s12, s5
	s_cbranch_scc1 .Lnat_dskip15
	s_cmp_gt_u32 s12, 3
	s_cselect_b32 s13, s7, 0
	s_add_i32 s13, s13, s12
	s_lshl_b32 s13, s13, 6
	s_and_b32 s0, s12, 1
	s_lshl_b32 s0, s0, 13
	s_bfe_u32 s1, s12, 0x10001
	s_mul_i32 s1, s1, 0xa000
	s_add_i32 s0, s0, s1
	s_add_i32 s0, s0, 0x4000
	s_add_i32 m0, s4, s0
	s_lshl_b32 s0, s13, 1
	s_mov_b32 s1, 0
	v_lshl_add_u64 v[182:183], v[144:145], 0, s[0:1]
	global_load_lds_dwordx4 v[182:183], off
.Lnat_dskip15:
	s_add_i32 s12, s89, 3
	s_cmp_ge_u32 s12, s5
	s_cbranch_scc1 .Lnat_dskip16
	s_cmp_gt_u32 s12, 3
	s_cselect_b32 s13, s7, 0
	s_add_i32 s13, s13, s12
	s_lshl_b32 s13, s13, 6
	s_and_b32 s0, s12, 1
	s_lshl_b32 s0, s0, 13
	s_bfe_u32 s1, s12, 0x10001
	s_mul_i32 s1, s1, 0xa000
	s_add_i32 s0, s0, s1
	s_add_i32 s0, s0, 0x4000
	s_add_i32 m0, s4, s0
	s_lshl_b32 s0, s13, 1
	s_mov_b32 s1, 0
	v_lshl_add_u64 v[182:183], v[144:145], 0, s[0:1]
	global_load_lds_dwordx4 v[182:183], off
.Lnat_dskip16:
	s_add_i32 s12, s89, 2
	s_cmp_ge_u32 s12, s5
	s_cbranch_scc1 .Lnat_noqk17
	s_add_i32 s12, s89, 2
	s_cmp_lt_u32 s12, 4
	s_cbranch_scc1 .Lnat_act19
	s_add_i32 s12, s12, s7
	s_add_i32 s12, s12, -4
	s_cmp_lt_i32 s12, s91
	s_cbranch_scc1 .Lnat_noqk17
	v_readlane_b32 s13, v253, 10
	s_cmp_ge_i32 s12, s13
	s_cbranch_scc1 .Lnat_noqk17
.Lnat_act19:
	s_add_i32 s12, s89, 2
	s_and_b32 s0, s12, 1
	s_lshl_b32 s0, s0, 13
	s_bfe_u32 s1, s12, 0x10001
	s_mul_i32 s1, s1, 0xa000
	s_add_i32 s0, s0, s1
	v_add_u32_e32 v174, s0, v156
	v_add_u32_e32 v175, s0, v157
	v_add_u32_e32 v176, s0, v160
	v_add_u32_e32 v177, s0, v161
	ds_read_b128 v[98:101], v174
	ds_read_b128 v[102:105], v174 offset:4096
	ds_read_b128 v[106:109], v175
	ds_read_b128 v[110:113], v175 offset:4096
	s_setprio 1
	s_waitcnt lgkmcnt(3)
	v_mfma_f32_32x32x16_bf16 v[50:65], v[98:101], v[114:117], v[34:49]
	ds_read_b128 v[98:101], v176
	s_waitcnt lgkmcnt(3)
	v_mfma_f32_32x32x16_bf16 v[66:81], v[102:105], v[114:117], v[34:49]
	ds_read_b128 v[102:105], v176 offset:4096
	s_waitcnt lgkmcnt(3)
	v_mfma_f32_32x32x16_bf16 v[50:65], v[106:109], v[118:121], v[50:65]
	ds_read_b128 v[106:109], v177
	s_waitcnt lgkmcnt(3)
	v_mfma_f32_32x32x16_bf16 v[66:81], v[110:113], v[118:121], v[66:81]
	ds_read_b128 v[110:113], v177 offset:4096
	s_waitcnt lgkmcnt(3)
	v_mfma_f32_32x32x16_bf16 v[50:65], v[98:101], v[122:125], v[50:65]
	s_waitcnt lgkmcnt(2)
	v_mfma_f32_32x32x16_bf16 v[66:81], v[102:105], v[122:125], v[66:81]
	s_waitcnt lgkmcnt(1)
	v_mfma_f32_32x32x16_bf16 v[50:65], v[106:109], v[126:129], v[50:65]
	s_waitcnt lgkmcnt(0)
	v_mfma_f32_32x32x16_bf16 v[66:81], v[110:113], v[126:129], v[66:81]
	s_setprio 0
.Lnat_noqk17:
	s_add_i32 s12, s89, 1
	s_cmp_lt_u32 s12, 4
	s_cbranch_scc1 .Lnat_act20
	s_add_i32 s12, s12, s7
	s_add_i32 s12, s12, -4
	s_cmp_lt_i32 s12, s91
	s_cbranch_scc1 .Lnat_nopv18
	v_readlane_b32 s13, v253, 10
	s_cmp_ge_i32 s12, s13
	s_cbranch_scc1 .Lnat_nopv18
.Lnat_act20:
	s_add_i32 s12, s89, 1
	s_and_b32 s0, s12, 1
	s_lshl_b32 s0, s0, 13
	s_bfe_u32 s1, s12, 0x10001
	s_mul_i32 s1, s1, 0xa000
	s_add_i32 s0, s0, s1
	s_add_i32 s0, s0, 0x4000
	v_add_u32_e32 v178, s0, v162
	v_add_u32_e32 v179, s0, v163
	v_add_u32_e32 v180, s0, v164
	v_add_u32_e32 v181, s0, v165
	ds_read_b128 v[98:101], v178
	ds_read_b128 v[102:105], v178 offset:4096
	ds_read_b128 v[106:109], v179
	ds_read_b128 v[110:113], v179 offset:4096
	s_setprio 1
	s_waitcnt lgkmcnt(3)
	v_mfma_f32_32x32x16_bf16 v[2:17], v[98:101], v[82:85], v[2:17]
	ds_read_b128 v[98:101], v180
	s_waitcnt lgkmcnt(3)
	v_mfma_f32_32x32x16_bf16 v[18:33], v[102:105], v[82:85], v[18:33]
	ds_read_b128 v[102:105], v180 offset:4096
	s_waitcnt lgkmcnt(3)
	v_mfma_f32_32x32x16_bf16 v[2:17], v[106:109], v[86:89], v[2:17]
	ds_read_b128 v[106:109], v181
	s_waitcnt lgkmcnt(3)
	v_mfma_f32_32x32x16_bf16 v[18:33], v[110:113], v[86:89], v[18:33]
	ds_read_b128 v[110:113], v181 offset:4096
	s_waitcnt lgkmcnt(3)
	v_mfma_f32_32x32x16_bf16 v[2:17], v[98:101], v[90:93], v[2:17]
	s_waitcnt lgkmcnt(2)
	v_mfma_f32_32x32x16_bf16 v[18:33], v[102:105], v[90:93], v[18:33]
	s_waitcnt lgkmcnt(1)
	v_mfma_f32_32x32x16_bf16 v[2:17], v[106:109], v[94:97], v[2:17]
	s_waitcnt lgkmcnt(0)
	v_mfma_f32_32x32x16_bf16 v[18:33], v[110:113], v[94:97], v[18:33]
	s_setprio 0

.Lnat_act22:
	s_mov_b64 s[8:9], 0
	s_mov_b64 s[10:11], 0
	s_add_i32 s12, s89, 2
	s_cmp_lt_u32 s12, 4
	s_cbranch_scc1 .Lnat_mdone23
	s_add_i32 s13, s12, s7
	s_add_i32 s13, s13, -4
	s_cmp_lt_i32 s13, s91
	s_cbranch_scc1 .Lnat_mout24
	v_readlane_b32 s0, v253, 10
	s_cmp_ge_i32 s13, s0
	s_cbranch_scc1 .Lnat_mout24
	v_readlane_b32 s0, v253, 6
	v_readlane_b32 s1, v254, 47
	s_add_i32 s0, s0, s1
	s_add_i32 s1, s7, s12
	s_add_i32 s1, s1, -1
	s_mul_i32 s1, s1, 31
	s_add_i32 s0, s0, s1
	v_lshl_add_u32 v178, s0, 2, v150
	v_lshl_add_u32 v178, v151, 2, v178
	v_sub_u32_e32 v176, 0, v150
	v_sub_u32_e64 v176, v176, 32 clamp
	v_min_u32_e32 v176, 0xc0, v176
	v_lshlrev_b32_e32 v177, 2, v151
	v_sub_u32_e32 v176, v177, v176
	ds_read_b32 v130, v178 offset:32828
	ds_read_b32 v131, v178 offset:32832
	ds_read_b32 v132, v178 offset:32836
	ds_read_b32 v133, v178 offset:32840
	ds_read_b32 v134, v178 offset:32844
	ds_read_b32 v135, v178 offset:32848
	ds_read_b32 v136, v178 offset:32852
	ds_read_b32 v137, v178 offset:32856
	ds_read_b32 v146, v178 offset:32892
	ds_read_b32 v148, v178 offset:32896
	ds_read_b32 v149, v178 offset:32900
	ds_read_b32 v166, v178 offset:32904
	ds_read_b32 v167, v178 offset:32908
	ds_read_b32 v168, v178 offset:32912
	ds_read_b32 v169, v178 offset:32916
	ds_read_b32 v0, v178 offset:32920
	s_waitcnt lgkmcnt(8)
	v_add_u32_e32 v184, 0, v176
	v_add_u32_e32 v185, 4, v176
	v_add_u32_e32 v174, 8, v176
	v_add_u32_e32 v175, 12, v176
	v_fmac_f32_e32 v50, 0x3fb8aa3b, v130
	v_fmac_f32_e32 v51, 0x3fb8aa3b, v131
	v_fmac_f32_e32 v52, 0x3fb8aa3b, v132
	v_fmac_f32_e32 v53, 0x3fb8aa3b, v133
	v_cmp_gt_u32_e32 vcc, 64, v184
	v_cmp_gt_u32_e64 s[0:1], 64, v185
	v_cmp_gt_u32_e64 s[12:13], 64, v174
	v_cmp_gt_u32_e64 s[14:15], 64, v175
	v_cndmask_b32_e32 v50, v205, v50, vcc
	v_cndmask_b32_e64 v51, v205, v51, s[0:1]
	v_cndmask_b32_e64 v52, v205, v52, s[12:13]
	v_cndmask_b32_e64 v53, v205, v53, s[14:15]
	v_add_u32_e32 v184, 16, v176
	v_add_u32_e32 v185, 20, v176
	v_add_u32_e32 v174, 24, v176
	v_add_u32_e32 v175, 28, v176
	v_fmac_f32_e32 v54, 0x3fb8aa3b, v134
	v_fmac_f32_e32 v55, 0x3fb8aa3b, v135
	v_fmac_f32_e32 v56, 0x3fb8aa3b, v136
	v_fmac_f32_e32 v57, 0x3fb8aa3b, v137
	v_cmp_gt_u32_e32 vcc, 64, v184
	v_cmp_gt_u32_e64 s[0:1], 64, v185
	v_cmp_gt_u32_e64 s[12:13], 64, v174
	v_cmp_gt_u32_e64 s[14:15], 64, v175
	v_cndmask_b32_e32 v54, v205, v54, vcc
	v_cndmask_b32_e64 v55, v205, v55, s[0:1]
	v_cndmask_b32_e64 v56, v205, v56, s[12:13]
	v_cndmask_b32_e64 v57, v205, v57, s[14:15]
	ds_read_b32 v130, v178 offset:32956
	ds_read_b32 v131, v178 offset:32960
	ds_read_b32 v132, v178 offset:32964
	ds_read_b32 v133, v178 offset:32968
	ds_read_b32 v134, v178 offset:32972
	ds_read_b32 v135, v178 offset:32976
	ds_read_b32 v136, v178 offset:32980
	ds_read_b32 v137, v178 offset:32984
	s_waitcnt lgkmcnt(8)
	v_add_u32_e32 v184, 64, v176
	v_add_u32_e32 v185, 68, v176
	v_add_u32_e32 v174, 72, v176
	v_add_u32_e32 v175, 76, v176
	v_fmac_f32_e32 v58, 0x3fb8aa3b, v146
	v_fmac_f32_e32 v59, 0x3fb8aa3b, v148
	v_fmac_f32_e32 v60, 0x3fb8aa3b, v149
	v_fmac_f32_e32 v61, 0x3fb8aa3b, v166
	v_cmp_gt_u32_e32 vcc, 64, v184
	v_cmp_gt_u32_e64 s[0:1], 64, v185
	v_cmp_gt_u32_e64 s[12:13], 64, v174
	v_cmp_gt_u32_e64 s[14:15], 64, v175
	v_cndmask_b32_e32 v58, v205, v58, vcc
	v_cndmask_b32_e64 v59, v205, v59, s[0:1]
	v_cndmask_b32_e64 v60, v205, v60, s[12:13]
	v_cndmask_b32_e64 v61, v205, v61, s[14:15]
	v_add_u32_e32 v184, 80, v176
	v_add_u32_e32 v185, 84, v176
	v_add_u32_e32 v174, 88, v176
	v_add_u32_e32 v175, 92, v176
	v_fmac_f32_e32 v62, 0x3fb8aa3b, v167
	v_fmac_f32_e32 v63, 0x3fb8aa3b, v168
	v_fmac_f32_e32 v64, 0x3fb8aa3b, v169
	v_fmac_f32_e32 v65, 0x3fb8aa3b, v0
	v_cmp_gt_u32_e32 vcc, 64, v184
	v_cmp_gt_u32_e64 s[0:1], 64, v185
	v_cmp_gt_u32_e64 s[12:13], 64, v174
	v_cmp_gt_u32_e64 s[14:15], 64, v175
	v_cndmask_b32_e32 v62, v205, v62, vcc
	v_cndmask_b32_e64 v63, v205, v63, s[0:1]
	v_cndmask_b32_e64 v64, v205, v64, s[12:13]
	v_cndmask_b32_e64 v65, v205, v65, s[14:15]
	ds_read_b32 v146, v178 offset:33020
	ds_read_b32 v148, v178 offset:33024
	ds_read_b32 v149, v178 offset:33028
	ds_read_b32 v166, v178 offset:33032
	ds_read_b32 v167, v178 offset:33036
	ds_read_b32 v168, v178 offset:33040
	ds_read_b32 v169, v178 offset:33044
	ds_read_b32 v0, v178 offset:33048
	s_waitcnt lgkmcnt(8)
	v_add_u32_e32 v184, 128, v176
	v_add_u32_e32 v185, 132, v176
	v_add_u32_e32 v174, 136, v176
	v_add_u32_e32 v175, 140, v176
	v_fmac_f32_e32 v66, 0x3fb8aa3b, v130
	v_fmac_f32_e32 v67, 0x3fb8aa3b, v131
	v_fmac_f32_e32 v68, 0x3fb8aa3b, v132
	v_fmac_f32_e32 v69, 0x3fb8aa3b, v133
	v_cmp_gt_u32_e32 vcc, 64, v184
	v_cmp_gt_u32_e64 s[0:1], 64, v185
	v_cmp_gt_u32_e64 s[12:13], 64, v174
	v_cmp_gt_u32_e64 s[14:15], 64, v175
	v_cndmask_b32_e32 v66, v205, v66, vcc
	v_cndmask_b32_e64 v67, v205, v67, s[0:1]
	v_cndmask_b32_e64 v68, v205, v68, s[12:13]
	v_cndmask_b32_e64 v69, v205, v69, s[14:15]
	v_add_u32_e32 v184, 144, v176
	v_add_u32_e32 v185, 148, v176
	v_add_u32_e32 v174, 152, v176
	v_add_u32_e32 v175, 156, v176
	v_fmac_f32_e32 v70, 0x3fb8aa3b, v134
	v_fmac_f32_e32 v71, 0x3fb8aa3b, v135
	v_fmac_f32_e32 v72, 0x3fb8aa3b, v136
	v_fmac_f32_e32 v73, 0x3fb8aa3b, v137
	v_cmp_gt_u32_e32 vcc, 64, v184
	v_cmp_gt_u32_e64 s[0:1], 64, v185
	v_cmp_gt_u32_e64 s[12:13], 64, v174
	v_cmp_gt_u32_e64 s[14:15], 64, v175
	v_cndmask_b32_e32 v70, v205, v70, vcc
	v_cndmask_b32_e64 v71, v205, v71, s[0:1]
	v_cndmask_b32_e64 v72, v205, v72, s[12:13]
	v_cndmask_b32_e64 v73, v205, v73, s[14:15]
	s_waitcnt lgkmcnt(0)
	v_add_u32_e32 v184, 192, v176
	v_add_u32_e32 v185, 196, v176
	v_add_u32_e32 v174, 200, v176
	v_add_u32_e32 v175, 204, v176
	v_fmac_f32_e32 v74, 0x3fb8aa3b, v146
	v_fmac_f32_e32 v75, 0x3fb8aa3b, v148
	v_fmac_f32_e32 v76, 0x3fb8aa3b, v149
	v_fmac_f32_e32 v77, 0x3fb8aa3b, v166
	v_cmp_gt_u32_e32 vcc, 64, v184
	v_cmp_gt_u32_e64 s[0:1], 64, v185
	v_cmp_gt_u32_e64 s[12:13], 64, v174
	v_cmp_gt_u32_e64 s[14:15], 64, v175
	v_cndmask_b32_e32 v74, v205, v74, vcc
	v_cndmask_b32_e64 v75, v205, v75, s[0:1]
	v_cndmask_b32_e64 v76, v205, v76, s[12:13]
	v_cndmask_b32_e64 v77, v205, v77, s[14:15]
	v_add_u32_e32 v184, 208, v176
	v_add_u32_e32 v185, 212, v176
	v_add_u32_e32 v174, 216, v176
	v_add_u32_e32 v175, 220, v176
	v_fmac_f32_e32 v78, 0x3fb8aa3b, v167
	v_fmac_f32_e32 v79, 0x3fb8aa3b, v168
	v_fmac_f32_e32 v80, 0x3fb8aa3b, v169
	v_fmac_f32_e32 v81, 0x3fb8aa3b, v0
	v_cmp_gt_u32_e32 vcc, 64, v184
	v_cmp_gt_u32_e64 s[0:1], 64, v185
	v_cmp_gt_u32_e64 s[12:13], 64, v174
	v_cmp_gt_u32_e64 s[14:15], 64, v175
	v_cndmask_b32_e32 v78, v205, v78, vcc
	v_cndmask_b32_e64 v79, v205, v79, s[0:1]
	v_cndmask_b32_e64 v80, v205, v80, s[12:13]
	v_cndmask_b32_e64 v81, v205, v81, s[14:15]
	s_branch .Lnat_mdone23

; #define LAS __attribute__((address_space(3)))
; #define ATT_LOADK(kt) do { const int k0_ = ATT_KEY0(kt); \
;         _Pragma("unroll") for (int p = 0; p < KPT; ++p) { const int c = tid + 512 * p; if (c < KCH) kr[p] = *(const GAS u32x4*)((const GAS char*)(Kb + (size_t)k0_ * DQK) + (unsigned)(c * 16)); } } while (0)
; #define ATT_LOADV(kt) do { const int k0_ = ATT_KEY0(kt); \
;         _Pragma("unroll") for (int p = 0; p < VPT; ++p) vr[p] = *(const GAS u32x4*)((const GAS char*)(Vb + k0_) + lvo[p]); } while (0)
; #define ATT_STOREK(buf) do { \
;         _Pragma("unroll") for (int p = 0; p < KPT; ++p) { const int c = tid + 512 * p; if (c < KCH) *(LAS u32x4*)(lds + (buf) * KBYTES + (c / CPR) * KS + (c % CPR) * 16) = kr[p]; } } while (0)
; #define ATT_STOREV(buf) do { \
;         _Pragma("unroll") for (int p = 0; p < VPT; ++p) { const int c = tid + 512 * p; *(LAS u32x4*)(lds + VOFF + (buf) * VBYTES + (c >> 3) * VS + (c & 7) * 16) = vr[p]; } } while (0)
; #define ATT_DMAK(kt, slot) do { const int k0_ = ATT_KEY0(kt); \
;         _Pragma("unroll") for (int i_ = 0; i_ < DKPT; ++i_) \
;             __builtin_amdgcn_global_load_lds((const unsigned*)((const char*)(Kb + (size_t)k0_ * DQK) + dko[i_]), (LAS unsigned*)(lds + (slot) * KBYTES + i_ * 8192 + w * 1024), 16, 0, 0); } while (0)
; template <int DQK, int DV, int NAT, int VSHIFT, int COMB> ...
;     ...
;         __syncthreads();
;         if (NAT) { for (int i = tid; i < 465; i += 512) rpb_s[i] = rpb[vh * 465 + i]; }
; #pragma unroll
;         for (int ks = 0; ks < DQK / 16; ++ks) { if (!QREG) *(LAS bf16x8*)(qs + ks * 1024) = qg[ks]; }
;         if (K128) { ATT_DMAK(0, 0); ATT_DMAV(0, 0); ATT_DMAK(1, 1); ATT_DMAV(1, 1); ATT_DMAK(2, 2); asm volatile("s_waitcnt vmcnt(0)" ::: "memory"); }
;         else if (DMA) { ATT_DMAK(0, 0); ATT_DMAV(0, 0); ATT_DMAK(1, 1); asm volatile("s_waitcnt vmcnt(0)" ::: "memory"); }
;         else { ATT_LOADK(0); ATT_STOREK(0); ATT_LOADV(0); ATT_STOREV(0); ATT_LOADK(1); ATT_STOREK(1); }
;         __syncthreads();
;         f32x16 sA0, sA1, sB0, sB1;
;         ATT_QK(sA0, sA1, 0);
;         __syncthreads();
;         for (int kt = 0; kt < nkt; kt += 2) {
;             ATT_STEP(sA0, sA1, sB0, sB1, kt, 0);
;             if (kt + 1 < nkt) ATT_STEP(sB0, sB1, sA0, sA1, kt + 1, 1);
;         }
.Lnat_vskip21:
.Lnat_tail:
	s_waitcnt vmcnt(0)
	s_barrier
	s_add_i32 s89, s89, 2
	s_cmp_lt_u32 s89, s5
	s_cbranch_scc1 .LBB0_546
